# GEMM phase prologues (in-proj, in-proj remainder, FFN1): the row-rstd stash no longer waits for its global load before the first LDS-DMA stages are issued (consume moved behind the first counted vmcnt
# baseline (speedup 1.0000x reference)
; #define LAS __attribute__((address_space(3)))
;     __device__ bool next(int i, Unit& u) const {
;         if (i >= icnt) return false; const long L = (long)(i + ioff) * G + c; if (L >= nwg) return false;
;         int wgid = (int)L; { const int q = nwg / NXCD, r = nwg % NXCD, xcd = wgid % NXCD, off = wgid / NXCD; wgid = (xcd < r ? xcd * (q + 1) : r * (q + 1) + (xcd - r) * q) + off; }
;         const int nig = WGM * nN, gid = wgid / nig, fm = gid * WGM, gsz = (nM - fm) < WGM ? (nM - fm) : WGM;
;         u.pm = fm + ((wgid % nig) % gsz); u.pn = (wgid % nig) / gsz; if (u.pn >= skip_lo) u.pn += skip_n; return true;
;     __device__ __forceinline__ void stash(unsigned long long v, LAS unsigned char* lds, int par, int tid) const { if (tid < 256) *(LAS float*)(lds + 131072 + par * 1024 + tid * 4) = rsqrtf((float)v * (1.f / (1048576.f * DM)) + EPS_); }
.LBB0_146:
	s_ashr_i32 s0, s2, 3
	s_add_i32 s0, s4, s0
	s_ashr_i32 s1, s0, 31
	s_lshr_b32 s1, s1, 24
	s_add_i32 s1, s0, s1
	s_ashr_i32 s2, s1, 8
	s_and_b32 s1, s1, 0xff00
	s_sub_i32 s0, s0, s1
	s_sext_i32_i16 s1, s0
	s_bfe_u32 s1, s1, 0x3001c
	s_lshl_b32 s3, s2, 3
	s_add_i32 s2, s0, s1
	s_and_b32 s1, s2, 0xfff8
	s_sub_i32 s0, s0, s1
	s_sext_i32_i16 s0, s0
	s_add_i32 s39, s3, s0
	s_movk_i32 s0, 0x100
	v_cmp_gt_i32_e64 s[4:5], s0, v144
	s_and_saveexec_b64 s[0:1], s[4:5]
	s_cbranch_execz .LBB0_148
	v_lshl_add_u32 v0, s39, 8, v144
	v_readlane_b32 s8, v254, 39
	s_waitcnt lgkmcnt(0)
	v_ashrrev_i32_e32 v1, 31, v0
	v_readlane_b32 s9, v254, 40
	s_mov_b32 s3, 0x800000
	s_nop 0
	v_lshl_add_u64 v[0:1], v[0:1], 3, s[8:9]
	global_load_dwordx2 v[222:223], v[0:1], off

; #define LAS __attribute__((address_space(3)))
; #define PG8_STAGE(bufoff, gbase, voff) do { _Pragma("unroll") for (int _i = 0; _i < 2; ++_i) \
;         __builtin_amdgcn_global_load_lds((const unsigned*)((const char*)(gbase) + (voff)[_i]), (LAS unsigned*)(lds + (bufoff) + ldsw + _i * 8192), 16, 0, 0); } while (0)
; #define PG8_WAIT_V(n) asm volatile("s_waitcnt vmcnt(" #n ")" ::: "memory")
; #define PG8_BAR __builtin_amdgcn_s_barrier()
; template <class Epi>
; __device__ __forceinline__ void gemm_phase(LAS unsigned char* lds, const Gemm g, const StaticOrder& S, const Epi& E) {
;     ...
;     if (Epi::PRE) E.stash(E.prefetch(cur.pm, tid), lds, 0, tid);
;     PG8_STAGE(PG8_SB(0, 0), cB, voffB); PG8_STAGE(PG8_SA(0, 0), cA, voffA); PG8_STAGE(PG8_SB(0, 1), cB + hstep, voffB); PG8_STAGE(PG8_SA(0, 1), cA + hstep, voffA);
;     if (wr == 1) PG8_BAR;
;     PG8_WAIT_V(4); PG8_BAR;
;     PG8_STAGE(PG8_SB(1, 0), cB + kstep, voffB); PG8_STAGE(PG8_SA(1, 0), cA + kstep, voffA); PG8_STAGE(PG8_SB(1, 1), cB + hstep + kstep, voffB);
;     PG8_WAIT_V(6); PG8_BAR;
;     __device__ __forceinline__ void stash(unsigned long long v, LAS unsigned char* lds, int par, int tid) const { if (tid < 256) *(LAS float*)(lds + 131072 + par * 1024 + tid * 4) = rsqrtf((float)v * (1.f / (1048576.f * DM)) + EPS_); }
.LBB0_150:
	s_mov_b64 s[12:13], 0x80
	s_add_i32 m0, s27, 0x18000
	v_lshl_add_u64 v[0:1], v[0:1], 0, s[12:13]
	s_waitcnt vmcnt(4)
	s_movk_i32 s92, 0x100
	v_cmp_gt_i32_e64 s[90:91], s92, v192
	s_and_saveexec_b64 s[92:93], s[90:91]
	v_ffbh_u32_e32 v228, v223
	v_min_u32_e32 v228, 32, v228
	v_lshlrev_b64 v[222:223], v228, v[222:223]
	v_min_u32_e32 v222, 1, v222
	v_or_b32_e32 v222, v223, v222
	v_cvt_f32_u32_e32 v222, v222
	v_sub_u32_e32 v223, 32, v228
	v_ldexp_f32 v222, v222, v223
	v_fmamk_f32 v222, v222, 0x30000000, v242
	v_mul_f32_e32 v223, 0x4b800000, v222
	s_mov_b32 s94, 0x800000
	v_cmp_gt_f32_e32 vcc, s94, v222
	s_nop 1
	v_cndmask_b32_e32 v222, v222, v223, vcc
	v_rsq_f32_e32 v222, v222
	v_lshl_add_u32 v223, v192, 2, 0
	v_add_u32_e32 v223, 0x20000, v223
	v_mul_f32_e32 v228, 0x45800000, v222
	v_cndmask_b32_e32 v222, v222, v228, vcc
	ds_write_b32 v223, v222
	s_or_b64 exec, exec, s[92:93]
	s_barrier
	global_load_lds_dwordx4 v[0:1], off
	v_lshl_add_u64 v[0:1], v[2:3], 0, s[12:13]
	s_add_i32 m0, s27, 0x1a000
	s_add_i32 s31, s27, 0x8000
	global_load_lds_dwordx4 v[0:1], off
	v_lshl_add_u64 v[0:1], v[4:5], 0, s[12:13]
	s_mov_b32 m0, s31
	s_add_i32 s33, s27, 0xa000
	global_load_lds_dwordx4 v[0:1], off
	v_lshl_add_u64 v[0:1], v[6:7], 0, s[12:13]
	s_mov_b32 m0, s33
	s_lshr_b32 s7, s7, 26
	global_load_lds_dwordx4 v[0:1], off
	s_add_i32 m0, s27, 0x1c000
	v_lshl_add_u64 v[0:1], v[8:9], 0, s[12:13]
	global_load_lds_dwordx4 v[0:1], off
	v_lshl_add_u64 v[0:1], v[10:11], 0, s[12:13]
	s_add_i32 m0, s27, 0x1e000
	s_add_i32 s7, s6, s7
	global_load_lds_dwordx4 v[0:1], off
	v_lshrrev_b32_e32 v1, 1, v144
	v_and_b32_e32 v0, 15, v144
	v_and_b32_e32 v1, 24, v1
	v_lshl_or_b32 v145, s9, 6, v0
	v_lshlrev_b32_e32 v2, 1, v1
	v_lshl_or_b32 v0, v0, 6, v2
	v_lshlrev_b32_e32 v2, 2, v145
	s_ashr_i32 s34, s7, 6
	s_lshl_b32 s7, s9, 13
	v_and_b32_e32 v3, 32, v2
	v_bitop3_b32 v3, v0, s7, v3 bitop3:0xde
	s_lshl_b32 s7, s10, 5
	s_sext_i32_i16 s40, s8
	s_and_b32 s8, s7, 0x60
	v_lshlrev_b32_e32 v4, 2, v144
	s_lshl_b32 s7, s8, 7
	v_and_b32_e32 v5, 32, v4
	v_bitop3_b32 v146, v0, s7, v5 bitop3:0xde
	v_add_u32_e32 v0, v17, v15
	v_or_b32_e32 v149, s8, v1
	v_add_lshl_u32 v0, v0, v16, 1
	v_mov_b32_e32 v1, v195
	s_waitcnt vmcnt(6)
	s_cmp_gt_i32 s6, 63
	v_lshl_add_u64 v[134:135], s[2:3], 0, v[0:1]
	v_add_u32_e32 v0, v14, v12
	s_cselect_b64 s[6:7], -1, 0
	s_add_i32 s9, 0, 0x20000
	v_add_lshl_u32 v0, v0, v13, 1
	s_add_i32 s35, s34, -2
	v_add_u32_e32 v147, s9, v2
	v_add_u32_e32 v148, s9, v4
	v_lshl_add_u64 v[136:137], s[2:3], 0, v[0:1]
	s_mov_b32 s41, 0
	v_add_u32_e32 v150, 0, v3
	s_barrier
	s_branch .LBB0_152

; #define LAS __attribute__((address_space(3)))
;     __device__ __forceinline__ void stash(unsigned long long v, LAS unsigned char* lds, int par, int tid) const { if (tid < 256) *(LAS float*)(lds + 131072 + par * 1024 + tid * 4) = rsqrtf((float)v * (1.f / (1048576.f * DM)) + EPS_); }
; __global__ void __launch_bounds__(512) mega_fwd(Params p) {
;     ...
;         case 2: {
;             if (bx < 192) { so.init(S_, 1536, 192, bx); pg8::Gemm g{B.CQN, (const bf16_t*)(Wl + WO_Q), S_, 1536, 512}; pg8::EpiQup e{(unsigned char*)B.Q, B.RC, B.RS}; pg8::gemm_phase(lds, g, so, e); }
;             else { so.init(S_, 512, 64, bx - 192, 0, 6); pg8::Gemm g{B.H, (const bf16_t*)(Wl + WO_IN), S_, NPROJP, DM}; pg8::EpiBf16<0> e{B.PROJ, NPROJP, ssqa}; pg8::gemm_phase(lds, g, so, e); }
.LBB0_391:
	s_and_b64 vcc, exec, s[0:1]
	s_cbranch_vccz .LBB0_465
	v_readlane_b32 s4, v254, 3
	s_cmpk_lt_i32 s4, 0xc0
	s_cselect_b64 s[0:1], -1, 0
	s_cmpk_gt_i32 s4, 0xbf
	s_mov_b64 s[4:5], -1
	s_cbranch_scc0 .LBB0_405
	v_readlane_b32 s4, v254, 3
	s_addk_i32 s4, 0xff40
	v_mov_b32_e32 v0, v192
	s_movk_i32 s26, 0x800
	v_readfirstlane_b32 s33, v0
	s_cmp_gt_u32 s4, 63
	s_cbranch_scc1 .LBB0_404
	s_lshr_b32 s30, s4, 3
	v_readlane_b32 s4, v254, 3
	s_lshl_b32 s4, s4, 2
	s_and_b32 s31, s4, 24
	s_movk_i32 s4, 0x100
	s_or_b32 s34, s30, s31
	v_cmp_gt_i32_e32 vcc, s4, v0
	s_and_saveexec_b64 s[4:5], vcc
	s_cbranch_execz .LBB0_396
	v_lshl_add_u32 v2, s34, 8, v0
	v_readlane_b32 s6, v254, 37
	v_ashrrev_i32_e32 v3, 31, v2
	v_readlane_b32 s7, v254, 38
	s_nop 1
	v_lshl_add_u64 v[2:3], v[2:3], 3, s[6:7]
	global_load_dwordx2 v[222:223], v[2:3], off
	s_mov_b32 s6, 0x800000

; #define PG8_STAGE(bufoff, gbase, voff) do { _Pragma("unroll") for (int _i = 0; _i < 2; ++_i) \
;         __builtin_amdgcn_global_load_lds((const unsigned*)((const char*)(gbase) + (voff)[_i]), (LAS unsigned*)(lds + (bufoff) + ldsw + _i * 8192), 16, 0, 0); } while (0)
; #define PG8_WAIT_V(n) asm volatile("s_waitcnt vmcnt(" #n ")" ::: "memory")
; #define PG8_BAR __builtin_amdgcn_s_barrier()
; template <class Epi>
; __device__ __forceinline__ void gemm_phase(LAS unsigned char* lds, const Gemm g, const StaticOrder& S, const Epi& E) {
;     ...
; #pragma unroll
;     for (int a = 0; a < 2; ++a)
; #pragma unroll
;         for (int b = 0; b < 2; ++b)
; #pragma unroll
;             for (int m = 0; m < 4; ++m)
; #pragma unroll
;                 for (int n = 0; n < 2; ++n) acc[a][b][m][n] = (f32x4){0.f, 0.f, 0.f, 0.f};
;     ...
;     PG8_STAGE(PG8_SB(0, 0), cB, voffB); PG8_STAGE(PG8_SA(0, 0), cA, voffA); PG8_STAGE(PG8_SB(0, 1), cB + hstep, voffB); PG8_STAGE(PG8_SA(0, 1), cA + hstep, voffA);
;     if (wr == 1) PG8_BAR;
;     PG8_WAIT_V(4); PG8_BAR;
;     PG8_STAGE(PG8_SB(1, 0), cB + kstep, voffB); PG8_STAGE(PG8_SA(1, 0), cA + kstep, voffA); PG8_STAGE(PG8_SB(1, 1), cB + hstep + kstep, voffB);
;     PG8_WAIT_V(6); PG8_BAR;
.LBB0_398:
	v_mov_b32_e32 v133, v195
	v_lshl_add_u64 v[10:11], s[28:29], 0, v[194:195]
	v_lshl_add_u64 v[12:13], s[28:29], 0, v[132:133]
	s_lshl_b32 s28, s36, 5
	v_lshl_add_u64 v[2:3], s[6:7], 0, v[194:195]
	v_and_b32_e32 v140, 15, v0
	v_lshrrev_b32_e32 v0, 1, v0
	s_and_b32 s36, s28, 0x60
	s_mov_b64 s[28:29], 0x80
	v_lshl_add_u64 v[4:5], s[6:7], 0, v[132:133]
	v_mov_b32_e32 v129, v195
	v_and_b32_e32 v139, 24, v0
	s_add_i32 m0, s38, 0x18000
	v_lshl_add_u64 v[0:1], v[2:3], 0, s[28:29]
	v_lshl_add_u64 v[6:7], s[4:5], 0, v[128:129]
	v_mov_b32_e32 v131, v195
	s_waitcnt vmcnt(4)
	s_movk_i32 s92, 0x100
	v_cmp_gt_i32_e64 s[90:91], s92, v192
	s_and_saveexec_b64 s[92:93], s[90:91]
	v_ffbh_u32_e32 v228, v223
	v_min_u32_e32 v228, 32, v228
	v_lshlrev_b64 v[222:223], v228, v[222:223]
	v_min_u32_e32 v222, 1, v222
	v_or_b32_e32 v222, v223, v222
	v_cvt_f32_u32_e32 v222, v222
	v_sub_u32_e32 v223, 32, v228
	v_ldexp_f32 v222, v222, v223
	v_fmamk_f32 v222, v222, 0x30000000, v242
	v_mul_f32_e32 v223, 0x4b800000, v222
	s_mov_b32 s94, 0x800000
	v_cmp_gt_f32_e32 vcc, s94, v222
	s_nop 1
	v_cndmask_b32_e32 v222, v222, v223, vcc
	v_rsq_f32_e32 v222, v222
	v_lshl_add_u32 v223, v192, 2, 0
	v_add_u32_e32 v223, 0x20000, v223
	v_mul_f32_e32 v228, 0x45800000, v222
	v_cndmask_b32_e32 v222, v222, v228, vcc
	ds_write_b32 v223, v222
	s_or_b64 exec, exec, s[92:93]
	s_barrier
	global_load_lds_dwordx4 v[0:1], off
	v_lshl_add_u64 v[0:1], v[4:5], 0, s[28:29]
	s_add_i32 m0, s38, 0x1a000
	s_add_i32 s42, s38, 0x8000
	v_lshl_add_u64 v[8:9], s[4:5], 0, v[130:131]
	global_load_lds_dwordx4 v[0:1], off
	v_lshl_add_u64 v[0:1], v[6:7], 0, s[28:29]
	s_mov_b32 m0, s42
	s_add_i32 s43, s38, 0xa000
	global_load_lds_dwordx4 v[0:1], off
	v_lshl_add_u64 v[0:1], v[8:9], 0, s[28:29]
	s_mov_b32 m0, s43
	v_mov_b32_e32 v127, 0
	global_load_lds_dwordx4 v[0:1], off
	s_add_i32 m0, s38, 0x1c000
	v_lshl_add_u64 v[0:1], v[10:11], 0, s[28:29]
	global_load_lds_dwordx4 v[0:1], off
	v_lshl_add_u64 v[0:1], v[12:13], 0, s[28:29]
	s_add_i32 m0, s38, 0x1e000
	v_lshl_or_b32 v138, s46, 6, v140
	global_load_lds_dwordx4 v[0:1], off
	s_waitcnt vmcnt(6)
	s_cmp_lt_i32 s26, 64
	v_mov_b32_e32 v126, v127
	v_mov_b32_e32 v125, v127
	v_mov_b32_e32 v124, v127
	v_mov_b32_e32 v123, v127
	v_mov_b32_e32 v122, v127
	v_mov_b32_e32 v121, v127
	v_mov_b32_e32 v120, v127
	v_mov_b32_e32 v111, v127
	v_mov_b32_e32 v110, v127
	v_mov_b32_e32 v109, v127
	v_mov_b32_e32 v108, v127
	v_mov_b32_e32 v107, v127
	v_mov_b32_e32 v106, v127
	v_mov_b32_e32 v105, v127
	v_mov_b32_e32 v104, v127
	v_mov_b32_e32 v95, v127
	v_mov_b32_e32 v94, v127
	v_mov_b32_e32 v93, v127
	v_mov_b32_e32 v92, v127
	v_mov_b32_e32 v91, v127
	v_mov_b32_e32 v90, v127
	v_mov_b32_e32 v89, v127
	v_mov_b32_e32 v88, v127
	v_mov_b32_e32 v79, v127
	v_mov_b32_e32 v78, v127
	v_mov_b32_e32 v77, v127
	v_mov_b32_e32 v76, v127
	v_mov_b32_e32 v75, v127
	v_mov_b32_e32 v74, v127
	v_mov_b32_e32 v73, v127
	v_mov_b32_e32 v72, v127
	v_mov_b32_e32 v119, v127
	v_mov_b32_e32 v118, v127
	v_mov_b32_e32 v117, v127
	v_mov_b32_e32 v116, v127
	v_mov_b32_e32 v115, v127
	v_mov_b32_e32 v114, v127
	v_mov_b32_e32 v113, v127
	v_mov_b32_e32 v112, v127
	v_mov_b32_e32 v103, v127
	v_mov_b32_e32 v102, v127
	v_mov_b32_e32 v101, v127
	v_mov_b32_e32 v100, v127
	v_mov_b32_e32 v99, v127
	v_mov_b32_e32 v98, v127
	v_mov_b32_e32 v97, v127
	v_mov_b32_e32 v96, v127
	v_mov_b32_e32 v87, v127
	v_mov_b32_e32 v86, v127
	v_mov_b32_e32 v85, v127
	v_mov_b32_e32 v84, v127
	v_mov_b32_e32 v83, v127
	v_mov_b32_e32 v82, v127
	v_mov_b32_e32 v81, v127
	v_mov_b32_e32 v80, v127
	v_mov_b32_e32 v71, v127
	v_mov_b32_e32 v70, v127
	v_mov_b32_e32 v69, v127
	v_mov_b32_e32 v68, v127
	v_mov_b32_e32 v67, v127
	v_mov_b32_e32 v66, v127
	v_mov_b32_e32 v65, v127
	v_mov_b32_e32 v64, v127
	v_mov_b32_e32 v63, v127
	v_mov_b32_e32 v62, v127
	v_mov_b32_e32 v61, v127
	v_mov_b32_e32 v60, v127
	v_mov_b32_e32 v59, v127
	v_mov_b32_e32 v58, v127
	v_mov_b32_e32 v57, v127
	v_mov_b32_e32 v56, v127
	v_mov_b32_e32 v47, v127
	v_mov_b32_e32 v46, v127
	v_mov_b32_e32 v45, v127
	v_mov_b32_e32 v44, v127
	v_mov_b32_e32 v43, v127
	v_mov_b32_e32 v42, v127
	v_mov_b32_e32 v41, v127
	v_mov_b32_e32 v40, v127
	v_mov_b32_e32 v31, v127
	v_mov_b32_e32 v30, v127
	v_mov_b32_e32 v29, v127
	v_mov_b32_e32 v28, v127
	v_mov_b32_e32 v27, v127
	v_mov_b32_e32 v26, v127
	v_mov_b32_e32 v25, v127
	v_mov_b32_e32 v24, v127
	v_mov_b32_e32 v15, v127
	v_mov_b32_e32 v14, v127
	v_mov_b32_e32 v13, v127
	v_mov_b32_e32 v12, v127
	v_mov_b32_e32 v11, v127
	v_mov_b32_e32 v10, v127
	v_mov_b32_e32 v9, v127
	v_mov_b32_e32 v8, v127
	v_mov_b32_e32 v55, v127
	v_mov_b32_e32 v54, v127
	v_mov_b32_e32 v53, v127
	v_mov_b32_e32 v52, v127
	v_mov_b32_e32 v51, v127
	v_mov_b32_e32 v50, v127
	v_mov_b32_e32 v49, v127
	v_mov_b32_e32 v48, v127
	v_mov_b32_e32 v39, v127
	v_mov_b32_e32 v38, v127
	v_mov_b32_e32 v37, v127
	v_mov_b32_e32 v36, v127
	v_mov_b32_e32 v35, v127
	v_mov_b32_e32 v34, v127
	v_mov_b32_e32 v33, v127
	v_mov_b32_e32 v32, v127
	v_mov_b32_e32 v23, v127
	v_mov_b32_e32 v22, v127
	v_mov_b32_e32 v21, v127
	v_mov_b32_e32 v20, v127
	v_mov_b32_e32 v19, v127
	v_mov_b32_e32 v18, v127
	v_mov_b32_e32 v17, v127
	v_mov_b32_e32 v16, v127
	v_mov_b32_e32 v7, v127
	v_mov_b32_e32 v6, v127
	v_mov_b32_e32 v5, v127
	v_mov_b32_e32 v4, v127
	v_mov_b32_e32 v3, v127
	v_mov_b32_e32 v2, v127
	v_mov_b32_e32 v1, v127
	v_mov_b32_e32 v0, v127
	s_barrier
; __device__ __forceinline__ int ltid() { int t = threadIdx.x; asm volatile("" : "+v"(t)); return t; }
; template <class Epi>
; __device__ __forceinline__ void gemm_phase(LAS unsigned char* lds, const Gemm g, const StaticOrder& S, const Epi& E) {
;     const int tid = ltid(), wid = __builtin_amdgcn_readfirstlane(tid >> 6), lane = tid & 63, wr = wid >> 2, wc = wid & 3, fr = lane & 15, fq = lane >> 4;
;     int K = g.K; asm volatile("" : "+s"(K)); const int nt = K / BK;
;     unsigned voffA[2], voffB[2];
; #pragma unroll
;     for (int i = 0; i < 2; ++i) { int R, C; stage_rc(tid * 16 + i * 8192, R, C); const int Rb = Epi::PERM ? ((R & ~31) + perm32(R & 31)) : R;
;         voffA[i] = (unsigned)(R * K + C) * 2u; voffB[i] = (unsigned)(Rb * K + C) * 2u; }
;     const size_t kstep = (size_t)(BK * 2);
;     const size_t hstep = (size_t)HALF * K * 2;
;     const size_t tstep = 2 * hstep;
;     const unsigned ldsw = (unsigned)wid * 1024u;
;     const int aoff = lds_byte(wr * 64 + fr, fq * 8), boff = lds_byte(wc * 32 + fr, fq * 8);
;     ...
;     for (;;) {
;         const bool has_next = S.next(ui + 1, nxt);
;         const char* nA = has_next ? (const char*)g.A + (size_t)nxt.pm * tstep : cA; const char* nB = has_next ? (const char*)g.Bt + (size_t)nxt.pn * tstep : cB;
;         for (int t = 0; t < nt; t += 2) {
	s_cbranch_scc1 .LBB0_401
	s_lshr_b32 s28, s27, 26
	s_add_i32 s28, s26, s28
	s_ashr_i32 s44, s28, 6
	v_lshlrev_b32_e32 v0, 6, v138
	v_lshlrev_b32_e32 v1, 1, v139
	s_movk_i32 s28, 0x3c0
	v_lshlrev_b32_e32 v2, 2, v138
	v_and_or_b32 v0, v0, s28, v1
	s_lshl_b32 s28, s46, 13
	v_and_b32_e32 v2, 32, v2
	v_bitop3_b32 v2, v0, s28, v2 bitop3:0xde
	v_lshl_or_b32 v0, v140, 6, v1
	v_lshlrev_b32_e32 v1, 2, v140
	s_lshl_b32 s28, s36, 7
	v_and_b32_e32 v1, 32, v1
	v_bitop3_b32 v140, v0, s28, v1 bitop3:0xde
	s_add_i32 s28, s30, s31
	v_readlane_b32 s30, v253, 36
	s_mov_b32 s29, s30
	s_lshl_b64 s[28:29], s[28:29], 9
	s_bitset1_b32 s28, 8
	s_mul_i32 s27, s28, s27
	s_mul_hi_u32 s30, s28, s26
	v_readlane_b32 s31, v253, 37
	s_add_i32 s27, s30, s27
	s_mul_i32 s29, s29, s26
	s_add_i32 s45, s44, -2
	s_add_i32 s27, s27, s29
	s_mul_i32 s28, s28, s26
	v_readlane_b32 s30, v254, 6
	v_add_u32_e32 v0, v142, v134
	v_readlane_b32 s31, v254, 7
	s_add_u32 s26, s30, s28
	v_add_lshl_u32 v0, v0, v135, 1
	v_mov_b32_e32 v1, v195
	s_addc_u32 s27, s31, s27
	v_lshl_add_u64 v[134:135], s[26:27], 0, v[0:1]
	v_add_u32_e32 v0, v141, v136
	v_add_lshl_u32 v0, v0, v137, 1
	v_lshl_add_u64 v[136:137], s[26:27], 0, v[0:1]
	v_mov_b32_e32 v0, 0
	s_mov_b32 s28, 0
	s_mov_b64 s[26:27], 0x1b200080
	v_add_u32_e32 v141, 0, v2
	v_mov_b32_e32 v1, v0
	v_mov_b32_e32 v2, v0
	v_mov_b32_e32 v3, v0
	v_mov_b32_e32 v4, v0
	v_mov_b32_e32 v5, v0
	v_mov_b32_e32 v6, v0
	v_mov_b32_e32 v7, v0
	v_mov_b32_e32 v16, v0
	v_mov_b32_e32 v17, v0
	v_mov_b32_e32 v18, v0
	v_mov_b32_e32 v19, v0
	v_mov_b32_e32 v20, v0
	v_mov_b32_e32 v21, v0
	v_mov_b32_e32 v22, v0
	v_mov_b32_e32 v23, v0
	v_mov_b32_e32 v32, v0
	v_mov_b32_e32 v33, v0
	v_mov_b32_e32 v34, v0
	v_mov_b32_e32 v35, v0
	v_mov_b32_e32 v36, v0
	v_mov_b32_e32 v37, v0
	v_mov_b32_e32 v38, v0
	v_mov_b32_e32 v39, v0
	v_mov_b32_e32 v48, v0
	v_mov_b32_e32 v49, v0
	v_mov_b32_e32 v50, v0
	v_mov_b32_e32 v51, v0
	v_mov_b32_e32 v52, v0
	v_mov_b32_e32 v53, v0
	v_mov_b32_e32 v54, v0
	v_mov_b32_e32 v55, v0
	v_mov_b32_e32 v8, v0
	v_mov_b32_e32 v9, v0
	v_mov_b32_e32 v10, v0
	v_mov_b32_e32 v11, v0
	v_mov_b32_e32 v12, v0
	v_mov_b32_e32 v13, v0
	v_mov_b32_e32 v14, v0
	v_mov_b32_e32 v15, v0
	v_mov_b32_e32 v24, v0
	v_mov_b32_e32 v25, v0
	v_mov_b32_e32 v26, v0
	v_mov_b32_e32 v27, v0
	v_mov_b32_e32 v28, v0
	v_mov_b32_e32 v29, v0
	v_mov_b32_e32 v30, v0
	v_mov_b32_e32 v31, v0
	v_mov_b32_e32 v40, v0
	v_mov_b32_e32 v41, v0
	v_mov_b32_e32 v42, v0
	v_mov_b32_e32 v43, v0
	v_mov_b32_e32 v44, v0
	v_mov_b32_e32 v45, v0
	v_mov_b32_e32 v46, v0
	v_mov_b32_e32 v47, v0
	v_mov_b32_e32 v56, v0
	v_mov_b32_e32 v57, v0
	v_mov_b32_e32 v58, v0
	v_mov_b32_e32 v59, v0
	v_mov_b32_e32 v60, v0
	v_mov_b32_e32 v61, v0
	v_mov_b32_e32 v62, v0
	v_mov_b32_e32 v63, v0
	v_mov_b32_e32 v64, v0
	v_mov_b32_e32 v65, v0
	v_mov_b32_e32 v66, v0
	v_mov_b32_e32 v67, v0
	v_mov_b32_e32 v68, v0
	v_mov_b32_e32 v69, v0
	v_mov_b32_e32 v70, v0
	v_mov_b32_e32 v71, v0
	v_mov_b32_e32 v80, v0
	v_mov_b32_e32 v81, v0
	v_mov_b32_e32 v82, v0
	v_mov_b32_e32 v83, v0
	v_mov_b32_e32 v84, v0
	v_mov_b32_e32 v85, v0
	v_mov_b32_e32 v86, v0
	v_mov_b32_e32 v87, v0
	v_mov_b32_e32 v96, v0
	v_mov_b32_e32 v97, v0
	v_mov_b32_e32 v98, v0
	v_mov_b32_e32 v99, v0
	v_mov_b32_e32 v100, v0
	v_mov_b32_e32 v101, v0
	v_mov_b32_e32 v102, v0
	v_mov_b32_e32 v103, v0
	v_mov_b32_e32 v112, v0
	v_mov_b32_e32 v113, v0
	v_mov_b32_e32 v114, v0
	v_mov_b32_e32 v115, v0
	v_mov_b32_e32 v116, v0
	v_mov_b32_e32 v117, v0
	v_mov_b32_e32 v118, v0
	v_mov_b32_e32 v119, v0
	v_mov_b32_e32 v72, v0
	v_mov_b32_e32 v73, v0
	v_mov_b32_e32 v74, v0
	v_mov_b32_e32 v75, v0
	v_mov_b32_e32 v76, v0
	v_mov_b32_e32 v77, v0
	v_mov_b32_e32 v78, v0
	v_mov_b32_e32 v79, v0
	v_mov_b32_e32 v88, v0
	v_mov_b32_e32 v89, v0
	v_mov_b32_e32 v90, v0
	v_mov_b32_e32 v91, v0
	v_mov_b32_e32 v92, v0
	v_mov_b32_e32 v93, v0
	v_mov_b32_e32 v94, v0
	v_mov_b32_e32 v95, v0
	v_mov_b32_e32 v104, v0
	v_mov_b32_e32 v105, v0
	v_mov_b32_e32 v106, v0
	v_mov_b32_e32 v107, v0
	v_mov_b32_e32 v108, v0
	v_mov_b32_e32 v109, v0
	v_mov_b32_e32 v110, v0
	v_mov_b32_e32 v111, v0
	v_mov_b32_e32 v120, v0
	v_mov_b32_e32 v121, v0
	v_mov_b32_e32 v122, v0
	v_mov_b32_e32 v123, v0
	v_mov_b32_e32 v124, v0
	v_mov_b32_e32 v125, v0
	v_mov_b32_e32 v126, v0
	v_mov_b32_e32 v127, v0
	s_mov_b64 s[50:51], 0x80

; #define LAS __attribute__((address_space(3)))
;     __device__ bool next(int i, Unit& u) const {
;         if (i >= icnt) return false; const long L = (long)(i + ioff) * G + c; if (L >= nwg) return false;
;         int wgid = (int)L; { const int q = nwg / NXCD, r = nwg % NXCD, xcd = wgid % NXCD, off = wgid / NXCD; wgid = (xcd < r ? xcd * (q + 1) : r * (q + 1) + (xcd - r) * q) + off; }
;         const int nig = WGM * nN, gid = wgid / nig, fm = gid * WGM, gsz = (nM - fm) < WGM ? (nM - fm) : WGM;
;         u.pm = fm + ((wgid % nig) % gsz); u.pn = (wgid % nig) / gsz; if (u.pn >= skip_lo) u.pn += skip_n; return true;
;     __device__ __forceinline__ void stash(unsigned long long v, LAS unsigned char* lds, int par, int tid) const { if (tid < 256) *(LAS float*)(lds + 131072 + par * 1024 + tid * 4) = rsqrtf((float)v * (1.f / (1048576.f * DM)) + EPS_); }
.LBB0_509:
	s_ashr_i32 s0, s2, 3
	s_add_i32 s0, s4, s0
	s_ashr_i32 s1, s0, 31
	s_lshr_b32 s1, s1, 25
	s_add_i32 s1, s0, s1
	s_ashr_i32 s2, s1, 7
	s_and_b32 s1, s1, 0xffffff80
	s_lshl_b32 s4, s2, 3
	s_sub_i32 s2, s0, s1
	s_bfe_i32 s0, s2, 0x80000
	s_bfe_u32 s0, s0, 0x3000c
	s_add_i32 s3, s2, s0
	s_and_b32 s0, s3, 0xf8
	s_sub_i32 s0, s2, s0
	s_sext_i32_i8 s0, s0
	s_add_i32 s37, s4, s0
	s_movk_i32 s0, 0x100
	v_cmp_gt_i32_e64 s[4:5], s0, v142
	s_and_saveexec_b64 s[0:1], s[4:5]
	s_cbranch_execz .LBB0_511
	v_lshl_add_u32 v0, s37, 8, v142
	v_readlane_b32 s8, v254, 37
	s_waitcnt lgkmcnt(0)
	v_ashrrev_i32_e32 v1, 31, v0
	v_readlane_b32 s9, v254, 38
	s_mov_b32 s7, 0x800000
	s_nop 0
	v_lshl_add_u64 v[0:1], v[0:1], 3, s[8:9]
	global_load_dwordx2 v[222:223], v[0:1], off

; #define LAS __attribute__((address_space(3)))
; #define PG8_STAGE(bufoff, gbase, voff) do { _Pragma("unroll") for (int _i = 0; _i < 2; ++_i) \
;         __builtin_amdgcn_global_load_lds((const unsigned*)((const char*)(gbase) + (voff)[_i]), (LAS unsigned*)(lds + (bufoff) + ldsw + _i * 8192), 16, 0, 0); } while (0)
; #define PG8_WAIT_V(n) asm volatile("s_waitcnt vmcnt(" #n ")" ::: "memory")
; #define PG8_BAR __builtin_amdgcn_s_barrier()
; template <class Epi>
; __device__ __forceinline__ void gemm_phase(LAS unsigned char* lds, const Gemm g, const StaticOrder& S, const Epi& E) {
;     ...
;     if (Epi::PRE) E.stash(E.prefetch(cur.pm, tid), lds, 0, tid);
;     PG8_STAGE(PG8_SB(0, 0), cB, voffB); PG8_STAGE(PG8_SA(0, 0), cA, voffA); PG8_STAGE(PG8_SB(0, 1), cB + hstep, voffB); PG8_STAGE(PG8_SA(0, 1), cA + hstep, voffA);
;     if (wr == 1) PG8_BAR;
;     PG8_WAIT_V(4); PG8_BAR;
;     PG8_STAGE(PG8_SB(1, 0), cB + kstep, voffB); PG8_STAGE(PG8_SA(1, 0), cA + kstep, voffA); PG8_STAGE(PG8_SB(1, 1), cB + hstep + kstep, voffB);
;     PG8_WAIT_V(6); PG8_BAR;
;     __device__ __forceinline__ void stash(unsigned long long v, LAS unsigned char* lds, int par, int tid) const { if (tid < 256) *(LAS float*)(lds + 131072 + par * 1024 + tid * 4) = rsqrtf((float)v * (1.f / (1048576.f * DM)) + EPS_); }
.LBB0_513:
	v_mov_b32_e32 v133, v195
	v_lshl_add_u64 v[6:7], s[18:19], 0, v[194:195]
	v_lshl_add_u64 v[14:15], s[8:9], 0, v[194:195]
	v_lshl_add_u64 v[16:17], s[8:9], 0, v[132:133]
	s_mov_b64 s[8:9], 0x80
	v_lshl_add_u64 v[8:9], s[18:19], 0, v[132:133]
	v_mov_b32_e32 v129, v195
	s_add_i32 m0, s25, 0x18000
	v_lshl_add_u64 v[6:7], v[6:7], 0, s[8:9]
	v_lshl_add_u64 v[10:11], s[16:17], 0, v[128:129]
	v_mov_b32_e32 v131, v195
	s_waitcnt vmcnt(4)
	s_movk_i32 s92, 0x100
	v_cmp_gt_i32_e64 s[90:91], s92, v192
	s_and_saveexec_b64 s[92:93], s[90:91]
	v_ffbh_u32_e32 v228, v223
	v_min_u32_e32 v228, 32, v228
	v_lshlrev_b64 v[222:223], v228, v[222:223]
	v_min_u32_e32 v222, 1, v222
	v_or_b32_e32 v222, v223, v222
	v_cvt_f32_u32_e32 v222, v222
	v_sub_u32_e32 v223, 32, v228
	v_ldexp_f32 v222, v222, v223
	v_fmamk_f32 v222, v222, 0x30000000, v242
	v_mul_f32_e32 v223, 0x4b800000, v222
	s_mov_b32 s94, 0x800000
	v_cmp_gt_f32_e32 vcc, s94, v222
	s_nop 1
	v_cndmask_b32_e32 v222, v222, v223, vcc
	v_rsq_f32_e32 v222, v222
	v_lshl_add_u32 v223, v192, 2, 0
	v_add_u32_e32 v223, 0x20000, v223
	v_mul_f32_e32 v228, 0x45800000, v222
	v_cndmask_b32_e32 v222, v222, v228, vcc
	ds_write_b32 v223, v222
	s_or_b64 exec, exec, s[92:93]
	s_barrier
	global_load_lds_dwordx4 v[6:7], off
	v_lshl_add_u64 v[6:7], v[8:9], 0, s[8:9]
	s_add_i32 m0, s25, 0x1a000
	s_add_i32 s29, s25, 0x8000
	v_lshl_add_u64 v[12:13], s[16:17], 0, v[130:131]
	global_load_lds_dwordx4 v[6:7], off
	v_lshl_add_u64 v[6:7], v[10:11], 0, s[8:9]
	s_mov_b32 m0, s29
	s_add_i32 s30, s25, 0xa000
	global_load_lds_dwordx4 v[6:7], off
	v_lshl_add_u64 v[6:7], v[12:13], 0, s[8:9]
	s_mov_b32 m0, s30
	s_lshr_b32 s7, s7, 26
	global_load_lds_dwordx4 v[6:7], off
	s_add_i32 m0, s25, 0x1c000
	v_lshl_add_u64 v[6:7], v[14:15], 0, s[8:9]
	global_load_lds_dwordx4 v[6:7], off
	v_lshl_add_u64 v[6:7], v[16:17], 0, s[8:9]
	s_add_i32 m0, s25, 0x1e000
	s_add_i32 s7, s6, s7
	global_load_lds_dwordx4 v[6:7], off
	v_lshrrev_b32_e32 v7, 1, v142
	v_and_b32_e32 v6, 15, v142
	v_and_b32_e32 v7, 24, v7
	v_lshl_or_b32 v143, s10, 6, v6
	v_lshlrev_b32_e32 v8, 1, v7
	v_lshl_or_b32 v6, v6, 6, v8
	v_lshlrev_b32_e32 v8, 2, v143
	s_ashr_i32 s31, s7, 6
	s_lshl_b32 s7, s10, 13
	v_and_b32_e32 v9, 32, v8
	v_bitop3_b32 v9, v6, s7, v9 bitop3:0xde
	s_lshl_b32 s7, s11, 5
	s_and_b32 s8, s7, 0x60
	s_lshl_b32 s7, s8, 7
	v_lshlrev_b32_e32 v10, 2, v142
	v_and_b32_e32 v11, 32, v10
	s_waitcnt vmcnt(6)
	s_cmp_gt_i32 s6, 63
	v_add_u32_e32 v3, v5, v3
	v_add_u32_e32 v0, v2, v0
	v_bitop3_b32 v144, v6, s7, v11 bitop3:0xde
	s_cselect_b64 s[6:7], -1, 0
	s_add_i32 s9, 0, 0x20000
	v_add_lshl_u32 v4, v3, v4, 1
	v_mov_b32_e32 v5, v195
	v_add_lshl_u32 v0, v0, v1, 1
	v_mov_b32_e32 v1, v195
	s_add_i32 s33, s31, -2
	v_add_u32_e32 v145, s9, v8
	v_add_u32_e32 v146, s9, v10
	v_or_b32_e32 v147, s8, v7
	v_lshl_add_u64 v[134:135], s[2:3], 0, v[4:5]
	v_lshl_add_u64 v[136:137], s[2:3], 0, v[0:1]
	s_mov_b32 s39, 0
	v_add_u32_e32 v148, 0, v9
	s_barrier
	s_branch .LBB0_515
